# prep: one-wave scalar set-up (softmax reference maxima, lambda) moved from block 0 to blocks G/2 and G/4, which have one transpose item fewer
# baseline (speedup 1.0000x reference)
; #define GAS __attribute__((address_space(1)))
; DI float shx(float v, int m, int lane) { return __builtin_bit_cast(float, __builtin_amdgcn_ds_bpermute((lane ^ m) << 2, __builtin_bit_cast(int, v))); }
; DI void phase_prep(const Ctx& C) {
;     ...
;     if (C.bid == 0 && wave == 0) {
;         float* misc = (float*)(ws + WS_MISC); const float* qkg = ARGP(C, 10); const float* rpbp = ARGP(C, 12); const float* snk = ARGP(C, 11);
;         for (int l = 0; l < 2; ++l) {
;             float gm[6];
; #pragma unroll
;             for (int j = 0; j < 6; ++j) { float v = fabsf(qkg[l * 384 + j * 64 + lane]);
; #pragma unroll
;                 for (int o = 1; o < 64; o <<= 1) v = fmaxf(v, shx(v, o, lane));
;                 gm[j] = v; }
;             float rm = 0.f;
;             { const GAS f32x4* rp4 = (const GAS f32x4*)(rpbp + l * 8 * 15 * 31);
; #pragma unroll 8
;               for (int i = lane; i < 930; i += 64) { const f32x4 v = rp4[i]; rm = fmaxf(fmaxf(rm, fmaxf(fabsf(v.x), fabsf(v.y))), fmaxf(fabsf(v.z), fabsf(v.w))); } }
;             float sm = lane < 8 ? snk[l * 8 + lane] : -1e30f;
; #pragma unroll
;             for (int o = 1; o < 64; o <<= 1) { rm = fmaxf(rm, shx(rm, o, lane)); sm = fmaxf(sm, shx(sm, o, lane)); }
;             if (lane == 0) { const float k = 64.f * QSCALE * 1.01f;
;                 misc[8 + 4 * l] = fmaxf(k * gm[0] * gm[1], sm * LOG2E); misc[9 + 4 * l] = k * gm[2] * gm[3] + rm * LOG2E; misc[10 + 4 * l] = k * gm[4] * gm[5]; }
;         }
;     }
;     if (C.bid == 0 && tid < 2) { const int l = tid; const float* dl = ARGP(C, 15) + l * 256; float s1 = 0.f, s2 = 0.f;
.LBB0_835:
	s_or_b64 exec, exec, s[0:1]
	v_readlane_b32 s0, v249, 51
	s_nop 3
	s_lshr_b32 s14, s0, 2
	s_lshr_b32 s0, s0, 1
	s_xor_b32 s0, s0, s2
	s_or_b32 s0, s0, s46
	s_cmp_eq_u32 s2, s14
	s_cselect_b64 s[14:15], -1, 0
	s_cmp_eq_u32 s0, 0
	s_cbranch_scc0 .LBB0_852
	v_readlane_b32 s0, v249, 22
	s_movk_i32 s6, 0x1c0
	s_movk_i32 s8, 0x1bf
	v_mov_b32_e32 v0, s0
	ds_read_b32 v0, v0
	v_readlane_b32 s0, v249, 23
	v_ashrrev_i32_e32 v205, 31, v204
	v_cmp_gt_i32_e64 s[10:11], 8, v204
	v_mov_b32_e32 v2, s0
	v_readlane_b32 s0, v249, 16
	s_waitcnt lgkmcnt(0)
	v_readfirstlane_b32 s16, v0
	s_mov_b32 s31, 0
	v_mov_b32_e32 v3, s0
	ds_read_b32 v2, v2
	ds_read_b32 v3, v3
	v_readlane_b32 s0, v249, 17
	v_cmp_eq_u32_e64 s[4:5], 0, v204
	v_xor_b32_e32 v8, 8, v156
	v_mov_b32_e32 v0, s0
	v_readlane_b32 s0, v249, 14
	ds_read_b32 v0, v0
	s_waitcnt lgkmcnt(0)
	v_readfirstlane_b32 s17, v2
	v_mov_b32_e32 v4, s0
	v_readlane_b32 s0, v249, 15
	ds_read_b32 v4, v4
	v_max_i32_e32 v2, 0x362, v204
	v_mov_b32_e32 v5, s0
	ds_read_b32 v5, v5
	v_sub_u32_e32 v2, v2, v204
	v_add_u32_e32 v2, 63, v2
	v_readfirstlane_b32 s2, v3
	v_lshrrev_b32_e32 v3, 6, v2
	v_add_u32_e32 v3, 1, v3
	s_waitcnt lgkmcnt(0)
	v_readfirstlane_b32 s18, v4
	s_movk_i32 s0, 0x3a2
	v_and_b32_e32 v4, 7, v3
	v_and_b32_e32 v3, 0x1c0, v2
	v_readfirstlane_b32 s30, v0
	v_readfirstlane_b32 s19, v5
	v_cmp_gt_i32_e64 s[0:1], s0, v204
	v_xor_b32_e32 v0, 4, v156
	v_xor_b32_e32 v9, 16, v156
	v_xor_b32_e32 v10, 32, v156
	v_xor_b32_e32 v11, 64, v156
	v_cmp_ne_u32_e64 s[6:7], s6, v3
	v_cmp_lt_u32_e64 s[8:9], s8, v2
	v_lshlrev_b64 v[2:3], 4, v[204:205]
	v_sub_u32_e32 v12, 0, v4
	s_mov_b64 s[20:21], -1
	s_branch .LBB0_838
